# v39: gate-merge branch-unit epilogue with scalar-stepped store base and 32-bit lane offset, stores issued as their data is ready
# baseline (speedup 1.0000x reference)
;   __device__ __forceinline__ void operator()(const f32x4 (&acc)[2][2][4][2], const Unit& u, int wr, int wc, int fr, int fq) const {
;     ...
;     if (s < 4) {
; #pragma unroll
;       for (int ai = 0; ai < 2; ++ai)
; #pragma unroll
;         for (int bj = 0; bj < 2; ++bj)
; #pragma unroll
;           for (int m = 0; m < 4; ++m) {
;             uint4 w;
;             w.x = pack2(acc[ai][bj][m][0][0], acc[ai][bj][m][0][1]); w.y = pack2(acc[ai][bj][m][0][2], acc[ai][bj][m][0][3]);
;             w.z = pack2(acc[ai][bj][m][1][0], acc[ai][bj][m][1][1]); w.w = pack2(acc[ai][bj][m][1][2], acc[ai][bj][m][1][3]);
;             brs[(size_t)(s * 16 + (ai * 2 + bj) * 4 + m) * 512 + tid] = w;
;           }
.LBB0_1417:
	s_lshl_b32 s2, s11, 17
	s_add_u32 s14, s48, s2
	s_addc_u32 s15, s49, 0
	v_lshlrev_b32_e32 v140, 4, v140
	s_mov_b64 s[100:101], s[14:15]
	v_cvt_pk_bf16_f32 v125, v124, v125
	v_cvt_pk_bf16_f32 v124, v122, v123
	v_cvt_pk_bf16_f32 v122, v126, v127
	v_cvt_pk_bf16_f32 v123, v128, v129
	global_store_dwordx4 v140, v[122:125], s[100:101]
	s_add_u32 s100, s100, 0x2000
	s_addc_u32 s101, s101, 0
	v_cvt_pk_bf16_f32 v117, v116, v117
	v_cvt_pk_bf16_f32 v116, v114, v115
	v_cvt_pk_bf16_f32 v114, v118, v119
	v_cvt_pk_bf16_f32 v115, v120, v121
	global_store_dwordx4 v140, v[114:117], s[100:101]
	s_add_u32 s100, s100, 0x2000
	s_addc_u32 s101, s101, 0
	v_cvt_pk_bf16_f32 v109, v108, v109
	v_cvt_pk_bf16_f32 v108, v106, v107
	v_cvt_pk_bf16_f32 v106, v110, v111
	v_cvt_pk_bf16_f32 v107, v112, v113
	global_store_dwordx4 v140, v[106:109], s[100:101]
	s_add_u32 s100, s100, 0x2000
	s_addc_u32 s101, s101, 0
	v_cvt_pk_bf16_f32 v101, v100, v101
	v_cvt_pk_bf16_f32 v100, v98, v99
	v_cvt_pk_bf16_f32 v98, v102, v103
	v_cvt_pk_bf16_f32 v99, v104, v105
	global_store_dwordx4 v140, v[98:101], s[100:101]
	s_add_u32 s100, s100, 0x2000
	s_addc_u32 s101, s101, 0
	v_cvt_pk_bf16_f32 v93, v92, v93
	v_cvt_pk_bf16_f32 v92, v90, v91
	v_cvt_pk_bf16_f32 v90, v94, v95
	v_cvt_pk_bf16_f32 v91, v96, v97
	global_store_dwordx4 v140, v[90:93], s[100:101]
	s_add_u32 s100, s100, 0x2000
	s_addc_u32 s101, s101, 0
	v_cvt_pk_bf16_f32 v85, v84, v85
	v_cvt_pk_bf16_f32 v84, v82, v83
	v_cvt_pk_bf16_f32 v82, v86, v87
	v_cvt_pk_bf16_f32 v83, v88, v89
	global_store_dwordx4 v140, v[82:85], s[100:101]
	s_add_u32 s100, s100, 0x2000
	s_addc_u32 s101, s101, 0
	v_cvt_pk_bf16_f32 v77, v76, v77
	v_cvt_pk_bf16_f32 v76, v74, v75
	v_cvt_pk_bf16_f32 v74, v78, v79
	v_cvt_pk_bf16_f32 v75, v80, v81
	global_store_dwordx4 v140, v[74:77], s[100:101]
	s_add_u32 s100, s100, 0x2000
	s_addc_u32 s101, s101, 0
	v_cvt_pk_bf16_f32 v69, v68, v69
	v_cvt_pk_bf16_f32 v68, v66, v67
	v_cvt_pk_bf16_f32 v66, v70, v71
	v_cvt_pk_bf16_f32 v67, v72, v73
	global_store_dwordx4 v140, v[66:69], s[100:101]
	s_add_u32 s100, s100, 0x2000
	s_addc_u32 s101, s101, 0
	v_cvt_pk_bf16_f32 v61, v60, v61
	v_cvt_pk_bf16_f32 v60, v58, v59
	v_cvt_pk_bf16_f32 v58, v62, v63
	v_cvt_pk_bf16_f32 v59, v64, v65
	global_store_dwordx4 v140, v[58:61], s[100:101]
	s_add_u32 s100, s100, 0x2000
	s_addc_u32 s101, s101, 0
	v_cvt_pk_bf16_f32 v53, v52, v53
	v_cvt_pk_bf16_f32 v52, v50, v51
	v_cvt_pk_bf16_f32 v50, v54, v55
	v_cvt_pk_bf16_f32 v51, v56, v57
	global_store_dwordx4 v140, v[50:53], s[100:101]
	s_add_u32 s100, s100, 0x2000
	s_addc_u32 s101, s101, 0
	v_cvt_pk_bf16_f32 v45, v44, v45
	v_cvt_pk_bf16_f32 v44, v42, v43
	v_cvt_pk_bf16_f32 v42, v46, v47
	v_cvt_pk_bf16_f32 v43, v48, v49
	global_store_dwordx4 v140, v[42:45], s[100:101]
	s_add_u32 s100, s100, 0x2000
	s_addc_u32 s101, s101, 0
	v_cvt_pk_bf16_f32 v37, v36, v37
	v_cvt_pk_bf16_f32 v36, v34, v35
	v_cvt_pk_bf16_f32 v34, v38, v39
	v_cvt_pk_bf16_f32 v35, v40, v41
	global_store_dwordx4 v140, v[34:37], s[100:101]
	s_add_u32 s100, s100, 0x2000
	s_addc_u32 s101, s101, 0
	v_cvt_pk_bf16_f32 v29, v28, v29
	v_cvt_pk_bf16_f32 v28, v26, v27
	v_cvt_pk_bf16_f32 v26, v30, v31
	v_cvt_pk_bf16_f32 v27, v32, v33
	global_store_dwordx4 v140, v[26:29], s[100:101]
	s_add_u32 s100, s100, 0x2000
	s_addc_u32 s101, s101, 0
	v_cvt_pk_bf16_f32 v21, v20, v21
	v_cvt_pk_bf16_f32 v20, v18, v19
	v_cvt_pk_bf16_f32 v18, v22, v23
	v_cvt_pk_bf16_f32 v19, v24, v25
	global_store_dwordx4 v140, v[18:21], s[100:101]
	s_add_u32 s100, s100, 0x2000
	s_addc_u32 s101, s101, 0
	v_cvt_pk_bf16_f32 v13, v12, v13
	v_cvt_pk_bf16_f32 v12, v10, v11
	v_cvt_pk_bf16_f32 v10, v14, v15
	v_cvt_pk_bf16_f32 v11, v16, v17
	global_store_dwordx4 v140, v[10:13], s[100:101]
	s_add_u32 s100, s100, 0x2000
	s_addc_u32 s101, s101, 0
	v_cvt_pk_bf16_f32 v5, v4, v5
	v_cvt_pk_bf16_f32 v4, v2, v3
	v_cvt_pk_bf16_f32 v2, v6, v7
	v_cvt_pk_bf16_f32 v3, v8, v9
	global_store_dwordx4 v140, v[2:5], s[100:101]
	s_mov_b32 s2, 0x1a000
	s_and_b64 vcc, exec, s[4:5]
	s_mov_b64 s[4:5], -1
	s_cbranch_vccnz .LBB0_1401
